# gdn_scan plain-mode state stores: tile pairs exchanged between 16-lane rows (v_permlane16_swap) and written as one dwordx4 per pair (64-byte runs, half the store instructions); counted waits re-derive
# speedup vs baseline: 1.0116x; 1.0116x over previous
; DI void gdn_scan(CP c, int l, int seq, int h, int mode, unsigned char* sm) {
;     ...
;     for (int n = 0; n < nsteps; n += 2) {
;         SC_STEP(P, n);
;         if (n + 1 < nsteps) SC_STEP(Q, n + 1);
;     }
.LBB0_551:
	s_add_u32 s12, s12, 32
	s_addc_u32 s13, s13, 0
	s_waitcnt lgkmcnt(0)
	s_barrier
	s_mov_b64 s[16:17], 0x20000
	s_add_u32 s8, s8, 32
	v_lshl_add_u64 v[90:91], v[90:91], 0, s[16:17]
	v_lshl_add_u64 v[92:93], v[92:93], 0, s[16:17]
	s_addc_u32 s9, s9, 0
	v_lshl_add_u64 v[94:95], v[94:95], 0, s[16:17]
	v_lshl_add_u64 v[96:97], v[96:97], 0, s[16:17]
	s_mov_b64 s[16:17], 0x40000
	v_lshl_add_u64 v[98:99], v[98:99], 0, s[16:17]
	v_lshl_add_u64 v[100:101], v[100:101], 0, s[16:17]
	s_cmpk_gt_u32 s18, 0x7d
	v_mov_b32_e32 v102, v144
	s_cbranch_scc1 .LBB0_620
.LBB0_552:
	v_cndmask_b32_e64 v103, 0, 1, s[22:23]
	v_lshl_add_u64 v[104:105], s[6:7], 0, v[100:101]
	v_cmp_ne_u32_e64 s[38:39], 1, v103
	s_and_b64 vcc, exec, s[38:39]
	s_cbranch_vccnz .Lscam_P
	v_and_b32_e32 v246, 16, v196
	v_lshrrev_b32_e32 v247, 1, v246
	v_add_u32_e32 v246, v246, v247
	v_add_co_u32_e32 v246, vcc, v104, v246
	s_nop 1
	v_addc_co_u32_e32 v247, vcc, 0, v105, vcc
	v_cvt_pk_bf16_f32 v236, v30, v31
	v_cvt_pk_bf16_f32 v237, v32, v33
	ds_write_b64 v131, v[236:237]
	v_cvt_pk_bf16_f32 v238, v18, v19
	v_cvt_pk_bf16_f32 v239, v20, v21
	ds_write_b64 v131, v[238:239] offset:32
	s_nop 1
	v_permlane16_swap_b32_e32 v236, v238
	v_permlane16_swap_b32_e32 v237, v239
	global_store_dwordx4 v[246:247], v[236:239], off
	v_cvt_pk_bf16_f32 v242, v10, v11
	v_cvt_pk_bf16_f32 v243, v12, v13
	ds_write_b64 v131, v[242:243] offset:64
	v_cvt_pk_bf16_f32 v244, v2, v3
	v_cvt_pk_bf16_f32 v245, v4, v5
	ds_write_b64 v131, v[244:245] offset:96
	s_nop 1
	v_permlane16_swap_b32_e32 v242, v244
	v_permlane16_swap_b32_e32 v243, v245
	global_store_dwordx4 v[246:247], v[242:245], off offset:64
	v_cvt_pk_bf16_f32 v236, v6, v7
	v_cvt_pk_bf16_f32 v237, v8, v9
	ds_write_b64 v131, v[236:237] offset:128
	v_cvt_pk_bf16_f32 v238, v14, v15
	v_cvt_pk_bf16_f32 v239, v16, v17
	ds_write_b64 v131, v[238:239] offset:160
	s_nop 1
	v_permlane16_swap_b32_e32 v236, v238
	v_permlane16_swap_b32_e32 v237, v239
	global_store_dwordx4 v[246:247], v[236:239], off offset:128
	v_cvt_pk_bf16_f32 v242, v22, v23
	v_cvt_pk_bf16_f32 v243, v24, v25
	ds_write_b64 v131, v[242:243] offset:192
	v_cvt_pk_bf16_f32 v244, v26, v27
	v_cvt_pk_bf16_f32 v245, v28, v29
	ds_write_b64 v131, v[244:245] offset:224
	s_nop 1
	v_permlane16_swap_b32_e32 v242, v244
	v_permlane16_swap_b32_e32 v243, v245
	global_store_dwordx4 v[246:247], v[242:245], off offset:192
	s_branch .LBB0_584
.Lscam_P:
	v_cvt_pk_bf16_f32 v106, v30, v31
	v_cvt_pk_bf16_f32 v107, v32, v33
	ds_write_b64 v131, v[106:107]
	v_lshl_add_u64 v[146:147], s[6:7], 0, v[98:99]
	global_store_short v[146:147], v106, off
	global_store_short_d16_hi v[146:147], v106, off offset:256
	global_store_short v[146:147], v107, off offset:512
	global_store_short_d16_hi v[146:147], v107, off offset:768
	v_cvt_pk_bf16_f32 v106, v18, v19
	v_cvt_pk_bf16_f32 v107, v20, v21
	ds_write_b64 v131, v[106:107] offset:32
	v_lshl_add_u64 v[146:147], s[6:7], 0, v[98:99]
	v_add_co_u32_e32 v146, vcc, 0x1000, v146
	s_nop 1
	v_addc_co_u32_e32 v147, vcc, 0, v147, vcc
	global_store_short v[146:147], v106, off
	global_store_short_d16_hi v[146:147], v106, off offset:256
	global_store_short v[146:147], v107, off offset:512
	global_store_short_d16_hi v[146:147], v107, off offset:768
	v_cvt_pk_bf16_f32 v106, v10, v11
	v_cvt_pk_bf16_f32 v107, v12, v13
	ds_write_b64 v131, v[106:107] offset:64
	v_lshl_add_u64 v[146:147], s[6:7], 0, v[98:99]
	v_add_co_u32_e32 v146, vcc, 0x2000, v146
	s_nop 1
	v_addc_co_u32_e32 v147, vcc, 0, v147, vcc
	global_store_short v[146:147], v106, off
	global_store_short_d16_hi v[146:147], v106, off offset:256
	global_store_short v[146:147], v107, off offset:512
	global_store_short_d16_hi v[146:147], v107, off offset:768
	v_cvt_pk_bf16_f32 v106, v2, v3
	v_cvt_pk_bf16_f32 v107, v4, v5
	ds_write_b64 v131, v[106:107] offset:96
	v_lshl_add_u64 v[146:147], s[6:7], 0, v[98:99]
	v_add_co_u32_e32 v146, vcc, 0x3000, v146
	s_nop 1
	v_addc_co_u32_e32 v147, vcc, 0, v147, vcc
	global_store_short v[146:147], v106, off
	global_store_short_d16_hi v[146:147], v106, off offset:256
	global_store_short v[146:147], v107, off offset:512
	global_store_short_d16_hi v[146:147], v107, off offset:768
	v_cvt_pk_bf16_f32 v106, v6, v7
	v_cvt_pk_bf16_f32 v107, v8, v9
	ds_write_b64 v131, v[106:107] offset:128
	v_lshl_add_u64 v[146:147], s[6:7], 0, v[98:99]
	v_add_co_u32_e32 v146, vcc, 0x4000, v146
	s_nop 1
	v_addc_co_u32_e32 v147, vcc, 0, v147, vcc
	global_store_short v[146:147], v106, off
	global_store_short_d16_hi v[146:147], v106, off offset:256
	global_store_short v[146:147], v107, off offset:512
	global_store_short_d16_hi v[146:147], v107, off offset:768
	v_cvt_pk_bf16_f32 v106, v14, v15
	v_cvt_pk_bf16_f32 v107, v16, v17
	ds_write_b64 v131, v[106:107] offset:160
	v_lshl_add_u64 v[146:147], s[6:7], 0, v[98:99]
	v_add_co_u32_e32 v146, vcc, 0x5000, v146
	s_nop 1
	v_addc_co_u32_e32 v147, vcc, 0, v147, vcc
	global_store_short v[146:147], v106, off
	global_store_short_d16_hi v[146:147], v106, off offset:256
	global_store_short v[146:147], v107, off offset:512
	global_store_short_d16_hi v[146:147], v107, off offset:768
	v_cvt_pk_bf16_f32 v106, v22, v23
	v_cvt_pk_bf16_f32 v107, v24, v25
	ds_write_b64 v131, v[106:107] offset:192
	v_lshl_add_u64 v[146:147], s[6:7], 0, v[98:99]
	v_add_co_u32_e32 v146, vcc, 0x6000, v146
	s_nop 1
	v_addc_co_u32_e32 v147, vcc, 0, v147, vcc
	global_store_short v[146:147], v106, off
	global_store_short_d16_hi v[146:147], v106, off offset:256
	global_store_short v[146:147], v107, off offset:512
	global_store_short_d16_hi v[146:147], v107, off offset:768
	v_cvt_pk_bf16_f32 v106, v26, v27
	v_cvt_pk_bf16_f32 v107, v28, v29
	ds_write_b64 v131, v[106:107] offset:224
	v_lshl_add_u64 v[146:147], s[6:7], 0, v[98:99]
	v_add_co_u32_e32 v146, vcc, 0x7000, v146
	s_nop 1
	v_addc_co_u32_e32 v147, vcc, 0, v147, vcc
	global_store_short v[146:147], v106, off
	global_store_short_d16_hi v[146:147], v106, off offset:256
	global_store_short v[146:147], v107, off offset:512
	global_store_short_d16_hi v[146:147], v107, off offset:768
.LBB0_584:
	v_add_u32_e32 v103, v132, v138
	v_add_u32_e32 v145, v129, v133
	s_waitcnt lgkmcnt(0)
	v_add_u32_e32 v106, v132, v139
	ds_read_b128 v[146:149], v145
	ds_read_b128 v[150:153], v145 offset:64
	ds_read_b128 v[154:157], v145 offset:128
	ds_read_b128 v[164:167], v145 offset:192
	ds_read_b128 v[172:175], v141
	ds_read_b128 v[176:179], v141 offset:64
	ds_read_b128 v[180:183], v141 offset:128
	ds_read_b128 v[184:187], v141 offset:192
	ds_read_b128 v[214:217], v141 offset:4352
	ds_read_b128 v[218:221], v141 offset:4416
	ds_read_b128 v[222:225], v141 offset:4480
	ds_read_b128 v[226:229], v141 offset:4544
	ds_read_u16 v103, v103
	ds_read_u16 v107, v106
	ds_read_u16 v159, v106 offset:272
	ds_read_u16 v171, v106 offset:544
	ds_read_u16 v192, v106 offset:4080
	ds_read_u16 v193, v106 offset:4352
	ds_read_u16 v204, v106 offset:4624
	ds_read_u16 v205, v106 offset:4896
	ds_read_u16 v206, v106 offset:8432
	ds_read_u16 v207, v106 offset:8704
	ds_read_u16 v213, v106 offset:8976
	ds_read_u16 v230, v106 offset:9248
	ds_read_u16 v231, v106 offset:12784
	ds_read_u16 v232, v106 offset:13056
	ds_read_u16 v233, v106 offset:13328
	ds_read_u16 v234, v106 offset:13600
	s_add_i32 s18, s18, 2
	s_waitcnt lgkmcnt(0)
	v_mfma_f32_16x16x32_bf16 v[172:175], v[172:175], v[146:149], 0
	v_lshlrev_b32_e32 v107, 16, v107
	v_lshlrev_b32_e32 v106, 16, v103
	v_mfma_f32_16x16x32_bf16 v[172:175], v[176:179], v[150:153], v[172:175]
	v_mfma_f32_16x16x32_bf16 v[172:175], v[180:183], v[154:157], v[172:175]
	v_mfma_f32_16x16x32_bf16 v[176:179], v[214:217], v[146:149], 0
	v_mfma_f32_16x16x32_bf16 v[172:175], v[184:187], v[164:167], v[172:175]
	v_mfma_f32_16x16x32_bf16 v[176:179], v[218:221], v[150:153], v[176:179]
	s_nop 6
	v_fma_f32 v106, v168, v106, -v172
	v_fma_f32 v107, v169, v107, -v173
	v_cvt_pk_bf16_f32 v158, v106, v107
	v_lshlrev_b32_e32 v107, 16, v171
	v_lshlrev_b32_e32 v106, 16, v159
	v_pk_fma_f32 v[106:107], v[168:169], v[106:107], v[174:175] neg_lo:[0,0,1] neg_hi:[0,0,1]
	v_mfma_f32_16x16x32_bf16 v[172:175], v[222:225], v[154:157], v[176:179]
	v_cvt_pk_bf16_f32 v159, v106, v107
	v_add_u32_e32 v107, v134, v130
	v_mfma_f32_16x16x32_bf16 v[172:175], v[226:229], v[164:167], v[172:175]
	v_lshlrev_b32_e32 v177, 16, v193
	v_lshlrev_b32_e32 v176, 16, v192
	s_nop 5
	v_pk_fma_f32 v[172:173], v[168:169], v[176:177], v[172:173] neg_lo:[0,0,1] neg_hi:[0,0,1]
	v_lshlrev_b32_e32 v177, 16, v205
	v_lshlrev_b32_e32 v176, 16, v204
	v_pk_fma_f32 v[174:175], v[168:169], v[176:177], v[174:175] neg_lo:[0,0,1] neg_hi:[0,0,1]
	v_cvt_pk_bf16_f32 v172, v172, v173
	v_cvt_pk_bf16_f32 v173, v174, v175
	ds_write2_b64 v107, v[158:159], v[172:173] offset1:4
	ds_read_b128 v[172:175], v141 offset:8704
	ds_read_b128 v[176:179], v141 offset:8768
	ds_read_b128 v[180:183], v141 offset:8832
	ds_read_b128 v[184:187], v141 offset:8896
	ds_read_b128 v[214:217], v141 offset:13056
	ds_read_b128 v[218:221], v141 offset:13120
	ds_read_b128 v[222:225], v141 offset:13184
	ds_read_b128 v[226:229], v141 offset:13248
	s_waitcnt lgkmcnt(7)
	v_mfma_f32_16x16x32_bf16 v[172:175], v[172:175], v[146:149], 0
	v_lshlrev_b32_e32 v159, 16, v207
	v_lshlrev_b32_e32 v158, 16, v206
	s_waitcnt lgkmcnt(3)
	v_mfma_f32_16x16x32_bf16 v[146:149], v[214:217], v[146:149], 0
	v_mfma_f32_16x16x32_bf16 v[172:175], v[176:179], v[150:153], v[172:175]
	s_waitcnt lgkmcnt(2)
	v_mfma_f32_16x16x32_bf16 v[146:149], v[218:221], v[150:153], v[146:149]
	v_lshlrev_b32_e32 v151, 16, v230
	v_lshlrev_b32_e32 v150, 16, v213
	v_mfma_f32_16x16x32_bf16 v[172:175], v[180:183], v[154:157], v[172:175]
	s_waitcnt lgkmcnt(1)
	v_mfma_f32_16x16x32_bf16 v[146:149], v[222:225], v[154:157], v[146:149]
	v_mfma_f32_16x16x32_bf16 v[172:175], v[184:187], v[164:167], v[172:175]
	s_waitcnt lgkmcnt(0)
	v_mfma_f32_16x16x32_bf16 v[146:149], v[226:229], v[164:167], v[146:149]
	s_nop 5
	v_fma_f32 v158, v168, v158, -v172
	v_fma_f32 v159, v169, v159, -v173
	v_pk_fma_f32 v[150:151], v[168:169], v[150:151], v[174:175] neg_lo:[0,0,1] neg_hi:[0,0,1]
	v_cvt_pk_bf16_f32 v158, v158, v159
	v_cvt_pk_bf16_f32 v159, v150, v151
	v_lshlrev_b32_e32 v151, 16, v232
	v_lshlrev_b32_e32 v150, 16, v231
	v_pk_fma_f32 v[146:147], v[168:169], v[150:151], v[146:147] neg_lo:[0,0,1] neg_hi:[0,0,1]
	v_lshlrev_b32_e32 v151, 16, v234
	v_lshlrev_b32_e32 v150, 16, v233
	v_pk_fma_f32 v[148:149], v[168:169], v[150:151], v[148:149] neg_lo:[0,0,1] neg_hi:[0,0,1]
	v_cvt_pk_bf16_f32 v146, v146, v147
	v_cvt_pk_bf16_f32 v147, v148, v149
	ds_write2_b64 v107, v[158:159], v[146:147] offset0:8 offset1:12
	ds_read_b128 v[148:151], v142 offset:34816
	ds_read_b128 v[152:155], v142 offset:34880
	ds_read_b128 v[156:159], v142 offset:37120
	ds_read_b128 v[164:167], v142 offset:37184
	ds_read_b128 v[172:175], v142 offset:39424
	ds_read_b128 v[176:179], v142 offset:39488
	ds_read_b128 v[180:183], v142 offset:41728
	ds_read_b128 v[184:187], v142 offset:41792
	v_add_u32_e32 v146, v134, v133
	s_waitcnt lgkmcnt(0)
	ds_read_b128 v[214:217], v146 offset:64
	ds_read_b128 v[218:221], v146
	v_pk_mul_f32 v[32:33], v[102:103], v[32:33] op_sel_hi:[0,1]
	v_pk_mul_f32 v[30:31], v[102:103], v[30:31] op_sel_hi:[0,1]
	v_pk_mul_f32 v[20:21], v[102:103], v[20:21] op_sel_hi:[0,1]
	v_pk_mul_f32 v[18:19], v[102:103], v[18:19] op_sel_hi:[0,1]
	v_pk_mul_f32 v[12:13], v[102:103], v[12:13] op_sel_hi:[0,1]
	v_pk_mul_f32 v[10:11], v[102:103], v[10:11] op_sel_hi:[0,1]
	v_pk_mul_f32 v[4:5], v[102:103], v[4:5] op_sel_hi:[0,1]
	v_pk_mul_f32 v[2:3], v[102:103], v[2:3] op_sel_hi:[0,1]
	s_waitcnt lgkmcnt(0)
	v_mfma_f32_16x16x32_bf16 v[30:33], v[148:151], v[218:221], v[30:33]
	v_mfma_f32_16x16x32_bf16 v[18:21], v[156:159], v[218:221], v[18:21]
	v_mfma_f32_16x16x32_bf16 v[10:13], v[172:175], v[218:221], v[10:13]
	v_mfma_f32_16x16x32_bf16 v[2:5], v[180:183], v[218:221], v[2:5]
	v_mfma_f32_16x16x32_bf16 v[30:33], v[152:155], v[214:217], v[30:33]
	v_mfma_f32_16x16x32_bf16 v[18:21], v[164:167], v[214:217], v[18:21]
	v_mfma_f32_16x16x32_bf16 v[10:13], v[176:179], v[214:217], v[10:13]
	v_mfma_f32_16x16x32_bf16 v[2:5], v[184:187], v[214:217], v[2:5]
	v_add_u32_e32 v147, v140, v133
	ds_read_b128 v[148:151], v147 offset:51008
	ds_read_b128 v[152:155], v147 offset:50944
	ds_read_b128 v[156:159], v143 offset:44096
	ds_read_b128 v[164:167], v143 offset:44032
	ds_read_b128 v[172:175], v147 offset:46400
	ds_read_b128 v[176:179], v147 offset:46336
	ds_read_b128 v[180:183], v147 offset:44096
	ds_read_b128 v[184:187], v147 offset:44032
	v_pk_mul_f32 v[8:9], v[102:103], v[8:9] op_sel_hi:[0,1]
	v_pk_mul_f32 v[6:7], v[102:103], v[6:7] op_sel_hi:[0,1]
	v_pk_mul_f32 v[16:17], v[102:103], v[16:17] op_sel_hi:[0,1]
	v_pk_mul_f32 v[14:15], v[102:103], v[14:15] op_sel_hi:[0,1]
	v_pk_mul_f32 v[24:25], v[102:103], v[24:25] op_sel_hi:[0,1]
	v_pk_mul_f32 v[22:23], v[102:103], v[22:23] op_sel_hi:[0,1]
	v_pk_mul_f32 v[28:29], v[102:103], v[28:29] op_sel_hi:[0,1]
	v_pk_mul_f32 v[26:27], v[102:103], v[26:27] op_sel_hi:[0,1]
	s_waitcnt lgkmcnt(0)
	v_mfma_f32_16x16x32_bf16 v[6:9], v[184:187], v[218:221], v[6:9]
	v_mfma_f32_16x16x32_bf16 v[14:17], v[176:179], v[218:221], v[14:17]
	v_mfma_f32_16x16x32_bf16 v[22:25], v[164:167], v[218:221], v[22:25]
	v_mfma_f32_16x16x32_bf16 v[26:29], v[152:155], v[218:221], v[26:29]
	v_mfma_f32_16x16x32_bf16 v[6:9], v[180:183], v[214:217], v[6:9]
	v_mfma_f32_16x16x32_bf16 v[14:17], v[172:175], v[214:217], v[14:17]
	v_mfma_f32_16x16x32_bf16 v[22:25], v[156:159], v[214:217], v[22:25]
	v_mfma_f32_16x16x32_bf16 v[26:29], v[148:151], v[214:217], v[26:29]
	s_cmpk_gt_u32 s18, 0x7c
	v_mov_b32_e32 v106, v88
	s_waitcnt vmcnt(8)
	ds_write_b128 v123, v[34:37] offset:17408
	ds_write_b128 v135, v[58:61]
	s_waitcnt vmcnt(7)
	ds_write_b128 v125, v[38:41] offset:17408
	ds_write_b128 v136, v[62:65]
	s_waitcnt vmcnt(6)
	ds_write_b128 v127, v[42:45] offset:53248
	ds_write_b128 v128, v[46:49] offset:53248
	s_cbranch_scc1 .LBB0_586
	v_lshl_add_u64 v[58:59], s[20:21], 0, v[96:97]
	v_add_co_u32_e32 v34, vcc, 0x156c4000, v58
	v_lshl_add_u64 v[60:61], s[20:21], 0, v[94:95]
	s_nop 0
	v_addc_co_u32_e32 v35, vcc, 0, v59, vcc
	v_add_co_u32_e32 v38, vcc, 0x156c4000, v60
	s_add_u32 s16, s20, s8
	s_nop 0
	v_addc_co_u32_e32 v39, vcc, 0, v61, vcc
	v_add_co_u32_e32 v42, vcc, 0x17ac4000, v58
	s_addc_u32 s17, s21, s9
	s_nop 0
	v_addc_co_u32_e32 v43, vcc, 0, v59, vcc
	v_add_co_u32_e32 v46, vcc, 0x17ac4000, v60
	global_load_dwordx4 v[34:37], v[34:35], off
	s_nop 0
	global_load_dwordx4 v[38:41], v[38:39], off
	v_addc_co_u32_e32 v47, vcc, 0, v61, vcc
	v_add_co_u32_e32 v58, vcc, 0x144c4000, v58
	global_load_dwordx4 v[42:45], v[42:43], off
	s_nop 0
	global_load_dwordx4 v[46:49], v[46:47], off
	v_addc_co_u32_e32 v59, vcc, 0, v59, vcc
	v_add_co_u32_e32 v62, vcc, 0x144c4000, v60
	s_nop 1
	v_addc_co_u32_e32 v63, vcc, 0, v61, vcc
	global_load_dwordx4 v[58:61], v[58:59], off
	s_nop 0
	global_load_dwordx4 v[62:65], v[62:63], off
	s_nop 0
	global_load_dword v106, v1, s[16:17]
.LBB0_586:
	s_waitcnt lgkmcnt(0)
	s_barrier
	s_and_b64 vcc, exec, s[38:39]
	s_cbranch_vccnz .Lscam_Q
	v_and_b32_e32 v246, 16, v196
	v_lshrrev_b32_e32 v247, 1, v246
	v_add_u32_e32 v246, v246, v247
	v_add_u32_e32 v246, 0x20000, v246
	v_add_co_u32_e32 v246, vcc, v104, v246
	s_nop 1
	v_addc_co_u32_e32 v247, vcc, 0, v105, vcc
	v_cvt_pk_bf16_f32 v236, v30, v31
	v_cvt_pk_bf16_f32 v237, v32, v33
	ds_write_b64 v131, v[236:237]
	v_cvt_pk_bf16_f32 v238, v18, v19
	v_cvt_pk_bf16_f32 v239, v20, v21
	ds_write_b64 v131, v[238:239] offset:32
	s_nop 1
	v_permlane16_swap_b32_e32 v236, v238
	v_permlane16_swap_b32_e32 v237, v239
	global_store_dwordx4 v[246:247], v[236:239], off
	v_cvt_pk_bf16_f32 v242, v10, v11
	v_cvt_pk_bf16_f32 v243, v12, v13
	ds_write_b64 v131, v[242:243] offset:64
	v_cvt_pk_bf16_f32 v244, v2, v3
	v_cvt_pk_bf16_f32 v245, v4, v5
	ds_write_b64 v131, v[244:245] offset:96
	s_nop 1
	v_permlane16_swap_b32_e32 v242, v244
	v_permlane16_swap_b32_e32 v243, v245
	global_store_dwordx4 v[246:247], v[242:245], off offset:64
	v_cvt_pk_bf16_f32 v236, v6, v7
	v_cvt_pk_bf16_f32 v237, v8, v9
	ds_write_b64 v131, v[236:237] offset:128
	v_cvt_pk_bf16_f32 v238, v14, v15
	v_cvt_pk_bf16_f32 v239, v16, v17
	ds_write_b64 v131, v[238:239] offset:160
	s_nop 1
	v_permlane16_swap_b32_e32 v236, v238
	v_permlane16_swap_b32_e32 v237, v239
	global_store_dwordx4 v[246:247], v[236:239], off offset:128
	v_cvt_pk_bf16_f32 v242, v22, v23
	v_cvt_pk_bf16_f32 v243, v24, v25
	ds_write_b64 v131, v[242:243] offset:192
	v_cvt_pk_bf16_f32 v244, v26, v27
	v_cvt_pk_bf16_f32 v245, v28, v29
	ds_write_b64 v131, v[244:245] offset:224
	s_nop 1
	v_permlane16_swap_b32_e32 v242, v244
	v_permlane16_swap_b32_e32 v243, v245
	global_store_dwordx4 v[246:247], v[242:245], off offset:192
	s_branch .LBB0_618
.Lscam_Q:
	v_cvt_pk_bf16_f32 v102, v30, v31
	v_cvt_pk_bf16_f32 v103, v32, v33
	ds_write_b64 v131, v[102:103]
	v_lshl_add_u64 v[148:149], s[6:7], 0, v[98:99]
	v_add_co_u32_e32 v148, vcc, 0x20000, v148
	s_nop 1
	v_addc_co_u32_e32 v149, vcc, 0, v149, vcc
	global_store_short v[148:149], v102, off
	global_store_short_d16_hi v[148:149], v102, off offset:256
	global_store_short v[148:149], v103, off offset:512
	global_store_short_d16_hi v[148:149], v103, off offset:768
	v_cvt_pk_bf16_f32 v102, v18, v19
	v_cvt_pk_bf16_f32 v103, v20, v21
	ds_write_b64 v131, v[102:103] offset:32
	v_lshl_add_u64 v[148:149], s[6:7], 0, v[98:99]
	v_add_co_u32_e32 v148, vcc, 0x21000, v148
	s_nop 1
	v_addc_co_u32_e32 v149, vcc, 0, v149, vcc
	global_store_short v[148:149], v102, off
	global_store_short_d16_hi v[148:149], v102, off offset:256
	global_store_short v[148:149], v103, off offset:512
	global_store_short_d16_hi v[148:149], v103, off offset:768
	v_cvt_pk_bf16_f32 v102, v10, v11
	v_cvt_pk_bf16_f32 v103, v12, v13
	ds_write_b64 v131, v[102:103] offset:64
	v_lshl_add_u64 v[148:149], s[6:7], 0, v[98:99]
	v_add_co_u32_e32 v148, vcc, 0x22000, v148
	s_nop 1
	v_addc_co_u32_e32 v149, vcc, 0, v149, vcc
	global_store_short v[148:149], v102, off
	global_store_short_d16_hi v[148:149], v102, off offset:256
	global_store_short v[148:149], v103, off offset:512
	global_store_short_d16_hi v[148:149], v103, off offset:768
	v_cvt_pk_bf16_f32 v102, v2, v3
	v_cvt_pk_bf16_f32 v103, v4, v5
	ds_write_b64 v131, v[102:103] offset:96
	v_lshl_add_u64 v[148:149], s[6:7], 0, v[98:99]
	v_add_co_u32_e32 v148, vcc, 0x23000, v148
	s_nop 1
	v_addc_co_u32_e32 v149, vcc, 0, v149, vcc
	global_store_short v[148:149], v102, off
	global_store_short_d16_hi v[148:149], v102, off offset:256
	global_store_short v[148:149], v103, off offset:512
	global_store_short_d16_hi v[148:149], v103, off offset:768
	v_cvt_pk_bf16_f32 v102, v6, v7
	v_cvt_pk_bf16_f32 v103, v8, v9
	ds_write_b64 v131, v[102:103] offset:128
	v_lshl_add_u64 v[148:149], s[6:7], 0, v[98:99]
	v_add_co_u32_e32 v148, vcc, 0x24000, v148
	s_nop 1
	v_addc_co_u32_e32 v149, vcc, 0, v149, vcc
	global_store_short v[148:149], v102, off
	global_store_short_d16_hi v[148:149], v102, off offset:256
	global_store_short v[148:149], v103, off offset:512
	global_store_short_d16_hi v[148:149], v103, off offset:768
	v_cvt_pk_bf16_f32 v102, v14, v15
	v_cvt_pk_bf16_f32 v103, v16, v17
	ds_write_b64 v131, v[102:103] offset:160
	v_lshl_add_u64 v[148:149], s[6:7], 0, v[98:99]
	v_add_co_u32_e32 v148, vcc, 0x25000, v148
	s_nop 1
	v_addc_co_u32_e32 v149, vcc, 0, v149, vcc
	global_store_short v[148:149], v102, off
	global_store_short_d16_hi v[148:149], v102, off offset:256
	global_store_short v[148:149], v103, off offset:512
	global_store_short_d16_hi v[148:149], v103, off offset:768
	v_cvt_pk_bf16_f32 v102, v22, v23
	v_cvt_pk_bf16_f32 v103, v24, v25
	ds_write_b64 v131, v[102:103] offset:192
	v_lshl_add_u64 v[148:149], s[6:7], 0, v[98:99]
	v_add_co_u32_e32 v148, vcc, 0x26000, v148
	s_nop 1
	v_addc_co_u32_e32 v149, vcc, 0, v149, vcc
	global_store_short v[148:149], v102, off
	global_store_short_d16_hi v[148:149], v102, off offset:256
	global_store_short v[148:149], v103, off offset:512
	global_store_short_d16_hi v[148:149], v103, off offset:768
	v_cvt_pk_bf16_f32 v102, v26, v27
	v_cvt_pk_bf16_f32 v103, v28, v29
	ds_write_b64 v131, v[102:103] offset:224
	v_lshl_add_u64 v[104:105], s[6:7], 0, v[98:99]
	v_add_co_u32_e32 v104, vcc, 0x27000, v104
	s_nop 1
	v_addc_co_u32_e32 v105, vcc, 0, v105, vcc
	global_store_short v[104:105], v102, off
	global_store_short_d16_hi v[104:105], v102, off offset:256
	global_store_short v[104:105], v103, off offset:512
	global_store_short_d16_hi v[104:105], v103, off offset:768
.LBB0_618:
	v_add_u32_e32 v171, v137, v138
	v_add_u32_e32 v192, v137, v139
	s_waitcnt lgkmcnt(0)
	ds_read_b128 v[102:105], v145
	ds_read_b128 v[148:151], v145 offset:64
	ds_read_b128 v[152:155], v145 offset:128
	ds_read_b128 v[156:159], v145 offset:192
	ds_read_b128 v[164:167], v141 offset:17408
	ds_read_b128 v[172:175], v141 offset:17472
	ds_read_b128 v[176:179], v141 offset:17536
	ds_read_b128 v[180:183], v141 offset:17600
	ds_read_b128 v[184:187], v141 offset:21760
	ds_read_b128 v[214:217], v141 offset:21824
	ds_read_b128 v[218:221], v141 offset:21888
	ds_read_b128 v[222:225], v141 offset:21952
	ds_read_u16 v145, v171
	ds_read_u16 v171, v192
	ds_read_u16 v193, v192 offset:272
	ds_read_u16 v204, v192 offset:544
	ds_read_u16 v205, v192 offset:4080
	ds_read_u16 v206, v192 offset:4352
	ds_read_u16 v207, v192 offset:4624
	ds_read_u16 v213, v192 offset:4896
	ds_read_u16 v226, v192 offset:8432
	ds_read_u16 v227, v192 offset:8704
	ds_read_u16 v228, v192 offset:8976
	ds_read_u16 v229, v192 offset:9248
	ds_read_u16 v230, v192 offset:12784
	ds_read_u16 v231, v192 offset:13056
	ds_read_u16 v232, v192 offset:13328
	ds_read_u16 v192, v192 offset:13600
	s_waitcnt lgkmcnt(14)
	v_mfma_f32_16x16x32_bf16 v[164:167], v[164:167], v[102:105], 0
	v_mfma_f32_16x16x32_bf16 v[164:167], v[172:175], v[148:151], v[164:167]
	v_mfma_f32_16x16x32_bf16 v[164:167], v[176:179], v[152:155], v[164:167]
	v_lshlrev_b32_e32 v177, 16, v171
	v_lshlrev_b32_e32 v176, 16, v145
	v_mfma_f32_16x16x32_bf16 v[172:175], v[184:187], v[102:105], 0
	v_mfma_f32_16x16x32_bf16 v[164:167], v[180:183], v[156:159], v[164:167]
	v_mfma_f32_16x16x32_bf16 v[172:175], v[214:217], v[148:151], v[172:175]
	s_nop 6
	v_fma_f32 v164, v168, v176, -v164
	v_fma_f32 v165, v169, v177, -v165
	v_cvt_pk_bf16_f32 v176, v164, v165
	s_waitcnt lgkmcnt(12)
	v_lshlrev_b32_e32 v165, 16, v204
	v_lshlrev_b32_e32 v164, 16, v193
	v_pk_fma_f32 v[178:179], v[168:169], v[164:165], v[166:167] neg_lo:[0,0,1] neg_hi:[0,0,1]
	v_mfma_f32_16x16x32_bf16 v[164:167], v[218:221], v[152:155], v[172:175]
	v_cvt_pk_bf16_f32 v177, v178, v179
	v_mfma_f32_16x16x32_bf16 v[164:167], v[222:225], v[156:159], v[164:167]
	s_waitcnt lgkmcnt(10)
	v_lshlrev_b32_e32 v173, 16, v206
	v_lshlrev_b32_e32 v172, 16, v205
	s_nop 4
	v_pk_fma_f32 v[164:165], v[168:169], v[172:173], v[164:165] neg_lo:[0,0,1] neg_hi:[0,0,1]
	s_waitcnt lgkmcnt(8)
	v_lshlrev_b32_e32 v173, 16, v213
	v_lshlrev_b32_e32 v172, 16, v207
	v_pk_fma_f32 v[166:167], v[168:169], v[172:173], v[166:167] neg_lo:[0,0,1] neg_hi:[0,0,1]
	v_cvt_pk_bf16_f32 v164, v164, v165
	v_cvt_pk_bf16_f32 v165, v166, v167
	ds_write2_b64 v107, v[176:177], v[164:165] offset1:4
	ds_read_b128 v[164:167], v141 offset:26112
	ds_read_b128 v[172:175], v141 offset:26176
	ds_read_b128 v[176:179], v141 offset:26240
	ds_read_b128 v[180:183], v141 offset:26304
	ds_read_b128 v[184:187], v141 offset:30464
	ds_read_b128 v[214:217], v141 offset:30528
	ds_read_b128 v[218:221], v141 offset:30592
	ds_read_b128 v[222:225], v141 offset:30656
	s_waitcnt lgkmcnt(7)
	v_mfma_f32_16x16x32_bf16 v[164:167], v[164:167], v[102:105], 0
	s_waitcnt lgkmcnt(3)
	v_mfma_f32_16x16x32_bf16 v[102:105], v[184:187], v[102:105], 0
	v_mfma_f32_16x16x32_bf16 v[164:167], v[172:175], v[148:151], v[164:167]
	v_lshlrev_b32_e32 v173, 16, v227
	v_lshlrev_b32_e32 v172, 16, v226
	s_waitcnt lgkmcnt(2)
	v_mfma_f32_16x16x32_bf16 v[102:105], v[214:217], v[148:151], v[102:105]
	v_lshlrev_b32_e32 v149, 16, v229
	v_lshlrev_b32_e32 v148, 16, v228
	v_mfma_f32_16x16x32_bf16 v[164:167], v[176:179], v[152:155], v[164:167]
	s_waitcnt lgkmcnt(1)
	v_mfma_f32_16x16x32_bf16 v[102:105], v[218:221], v[152:155], v[102:105]
	v_mfma_f32_16x16x32_bf16 v[164:167], v[180:183], v[156:159], v[164:167]
	s_waitcnt lgkmcnt(0)
	v_mfma_f32_16x16x32_bf16 v[102:105], v[222:225], v[156:159], v[102:105]
	s_nop 5
	v_fma_f32 v164, v168, v172, -v164
	v_fma_f32 v165, v169, v173, -v165
	v_pk_fma_f32 v[148:149], v[168:169], v[148:149], v[166:167] neg_lo:[0,0,1] neg_hi:[0,0,1]
	v_cvt_pk_bf16_f32 v164, v164, v165
	v_cvt_pk_bf16_f32 v165, v148, v149
	v_lshlrev_b32_e32 v149, 16, v231
	v_lshlrev_b32_e32 v148, 16, v230
	v_pk_fma_f32 v[102:103], v[168:169], v[148:149], v[102:103] neg_lo:[0,0,1] neg_hi:[0,0,1]
	v_lshlrev_b32_e32 v149, 16, v192
	v_lshlrev_b32_e32 v148, 16, v232
	v_pk_fma_f32 v[104:105], v[168:169], v[148:149], v[104:105] neg_lo:[0,0,1] neg_hi:[0,0,1]
	v_cvt_pk_bf16_f32 v102, v102, v103
	v_cvt_pk_bf16_f32 v103, v104, v105
	ds_write2_b64 v107, v[164:165], v[102:103] offset0:8 offset1:12
	ds_read_b128 v[102:105], v142 offset:53248
	ds_read_b128 v[148:151], v142 offset:53312
	ds_read_b128 v[152:155], v142 offset:55552
	ds_read_b128 v[156:159], v142 offset:55616
	ds_read_b128 v[164:167], v142 offset:57856
	ds_read_b128 v[172:175], v142 offset:57920
	ds_read_b128 v[176:179], v142 offset:60160
	ds_read_b128 v[180:183], v142 offset:60224
	s_waitcnt lgkmcnt(0)
	ds_read_b128 v[184:187], v146 offset:64
	ds_read_b128 v[214:217], v146
	v_pk_mul_f32 v[32:33], v[88:89], v[32:33] op_sel_hi:[0,1]
	v_pk_mul_f32 v[30:31], v[88:89], v[30:31] op_sel_hi:[0,1]
	v_pk_mul_f32 v[20:21], v[88:89], v[20:21] op_sel_hi:[0,1]
	v_pk_mul_f32 v[18:19], v[88:89], v[18:19] op_sel_hi:[0,1]
	v_pk_mul_f32 v[12:13], v[88:89], v[12:13] op_sel_hi:[0,1]
	v_pk_mul_f32 v[10:11], v[88:89], v[10:11] op_sel_hi:[0,1]
	v_pk_mul_f32 v[4:5], v[88:89], v[4:5] op_sel_hi:[0,1]
	v_pk_mul_f32 v[2:3], v[88:89], v[2:3] op_sel_hi:[0,1]
	s_waitcnt lgkmcnt(0)
	v_mfma_f32_16x16x32_bf16 v[30:33], v[102:105], v[214:217], v[30:33]
	v_mfma_f32_16x16x32_bf16 v[18:21], v[152:155], v[214:217], v[18:21]
	v_mfma_f32_16x16x32_bf16 v[10:13], v[164:167], v[214:217], v[10:13]
	v_mfma_f32_16x16x32_bf16 v[2:5], v[176:179], v[214:217], v[2:5]
	v_mfma_f32_16x16x32_bf16 v[30:33], v[148:151], v[184:187], v[30:33]
	v_mfma_f32_16x16x32_bf16 v[18:21], v[156:159], v[184:187], v[18:21]
	v_mfma_f32_16x16x32_bf16 v[10:13], v[172:175], v[184:187], v[10:13]
	v_mfma_f32_16x16x32_bf16 v[2:5], v[180:183], v[184:187], v[2:5]
	ds_read_b128 v[102:105], v0 offset:9280
	ds_read_b128 v[148:151], v0 offset:9216
	ds_read_b128 v[152:155], v143 offset:62528
	ds_read_b128 v[156:159], v143 offset:62464
	ds_read_b128 v[164:167], v147 offset:64832
	ds_read_b128 v[172:175], v147 offset:64768
	ds_read_b128 v[176:179], v147 offset:62528
	ds_read_b128 v[180:183], v147 offset:62464
	v_pk_mul_f32 v[8:9], v[88:89], v[8:9] op_sel_hi:[0,1]
	v_pk_mul_f32 v[6:7], v[88:89], v[6:7] op_sel_hi:[0,1]
	v_pk_mul_f32 v[16:17], v[88:89], v[16:17] op_sel_hi:[0,1]
	v_pk_mul_f32 v[14:15], v[88:89], v[14:15] op_sel_hi:[0,1]
	v_pk_mul_f32 v[24:25], v[88:89], v[24:25] op_sel_hi:[0,1]
	v_pk_mul_f32 v[22:23], v[88:89], v[22:23] op_sel_hi:[0,1]
	v_pk_mul_f32 v[28:29], v[88:89], v[28:29] op_sel_hi:[0,1]
	v_pk_mul_f32 v[26:27], v[88:89], v[26:27] op_sel_hi:[0,1]
	s_waitcnt lgkmcnt(0)
	v_mfma_f32_16x16x32_bf16 v[6:9], v[180:183], v[214:217], v[6:9]
	v_mfma_f32_16x16x32_bf16 v[14:17], v[172:175], v[214:217], v[14:17]
	v_mfma_f32_16x16x32_bf16 v[22:25], v[156:159], v[214:217], v[22:25]
	v_mfma_f32_16x16x32_bf16 v[26:29], v[148:151], v[214:217], v[26:29]
	v_mfma_f32_16x16x32_bf16 v[6:9], v[176:179], v[184:187], v[6:9]
	v_mfma_f32_16x16x32_bf16 v[14:17], v[164:167], v[184:187], v[14:17]
	v_mfma_f32_16x16x32_bf16 v[22:25], v[152:155], v[184:187], v[22:25]
	v_mfma_f32_16x16x32_bf16 v[26:29], v[102:105], v[184:187], v[26:29]
	s_cmpk_gt_u32 s18, 0x7b
	s_waitcnt vmcnt(4)
	v_mov_b32_e32 v144, v240
	v_mov_b32_e32 v88, v106
	ds_write_b128 v123, v[50:53]
	ds_write_b128 v124, v[74:77]
	ds_write_b128 v125, v[54:57]
	ds_write_b128 v126, v[78:81]
	ds_write_b128 v127, v[66:69] offset:34816
	ds_write_b128 v128, v[70:73] offset:34816
	s_cbranch_scc1 .LBB0_551
	v_lshl_add_u64 v[74:75], s[20:21], 0, v[92:93]
	v_add_co_u32_e32 v50, vcc, 0x156c4000, v74
	v_lshl_add_u64 v[76:77], s[20:21], 0, v[90:91]
	s_nop 0
	v_addc_co_u32_e32 v51, vcc, 0, v75, vcc
	v_add_co_u32_e32 v54, vcc, 0x156c4000, v76
	s_add_u32 s16, s20, s12
	s_nop 0
	v_addc_co_u32_e32 v55, vcc, 0, v77, vcc
	v_add_co_u32_e32 v66, vcc, 0x17ac4000, v74
	s_addc_u32 s17, s21, s13
	s_nop 0
	v_addc_co_u32_e32 v67, vcc, 0, v75, vcc
	v_add_co_u32_e32 v70, vcc, 0x17ac4000, v76
	global_load_dwordx4 v[50:53], v[50:51], off
	s_nop 0
	global_load_dwordx4 v[54:57], v[54:55], off
	v_addc_co_u32_e32 v71, vcc, 0, v77, vcc
	v_add_co_u32_e32 v74, vcc, 0x144c4000, v74
	global_load_dwordx4 v[66:69], v[66:67], off
	s_nop 0
	global_load_dwordx4 v[70:73], v[70:71], off
	v_addc_co_u32_e32 v75, vcc, 0, v75, vcc
	v_add_co_u32_e32 v78, vcc, 0x144c4000, v76
	s_nop 1
	v_addc_co_u32_e32 v79, vcc, 0, v77, vcc
	global_load_dwordx4 v[74:77], v[74:75], off
	s_nop 0
	global_load_dwordx4 v[78:81], v[78:79], off
	s_nop 0
	global_load_dword v240, v1, s[16:17]
	s_branch .LBB0_551
